# sub-LN phases: next row's two loads prefetched at the top of each row
# speedup vs baseline: 1.0000x; 1.0000x over previous
; #define in KArgIn()
; #define FRESH_IDS() const int tid = tid_fresh(wv), lane = tid & 63, wave = wv
; template <int l, int SEL> __device__ __forceinline__ void layer_body(const Args& args, LAS unsigned char* ldsp, unsigned char* lds, const int G, const int bx, const int vcu, const int wv) {
;     ...
;             FRESH_IDS();
;             const float lam_init = 0.8f - 0.6f * expf(-0.3f * (float)l);
;             const float a1 = wave_sum(in[5][l * 64 + lane] * in[6][l * 64 + lane]), a2 = wave_sum(in[7][l * 64 + lane] * in[8][l * 64 + lane]);
;             const float lam = expf(a1) - expf(a2) + lam_init;
;             const float* sg = in[9] + l * 128 + (lane & 15) * 8; float gsc[8];
; #pragma unroll
;             for (int i = 0; i < 8; ++i) gsc[i] = sg[i] * (1.f - lam_init);
;             const int gw = bx * NWAVES + wave, NGW = G * NWAVES;
;             for (int row = gw; row < M; row += NGW) {
;                 const v4u a = *(const v4u*)(q_odiff + (size_t)row * 512 + 8 * lane), b = *(const v4u*)(q_odiff + (size_t)(M + row) * 512 + 8 * lane);
.LBB0_596:
	s_or_b64 exec, exec, s[4:5]
	s_mov_b64 s[4:5], s[0:1]
	s_waitcnt lgkmcnt(0)
	s_barrier
	v_mbcnt_lo_u32_b32 v0, -1, 0
	v_mbcnt_hi_u32_b32 v0, -1, v0
	s_load_dwordx2 s[4:5], s[4:5], 0x28
	v_and_b32_e32 v2, 63, v0
	v_lshlrev_b32_e32 v1, 2, v2
	s_and_b64 vcc, exec, s[38:39]
	s_waitcnt lgkmcnt(0)
	global_load_dword v3, v1, s[4:5]
	s_mov_b64 s[4:5], s[0:1]
	s_load_dwordx2 s[4:5], s[4:5], 0x30
	s_waitcnt lgkmcnt(0)
	global_load_dword v4, v1, s[4:5]
	s_mov_b64 s[4:5], s[0:1]
	s_load_dwordx2 s[4:5], s[4:5], 0x38
	s_waitcnt lgkmcnt(0)
	global_load_dword v11, v1, s[4:5]
	s_mov_b64 s[4:5], s[0:1]
	s_load_dwordx2 s[4:5], s[4:5], 0x40
	s_waitcnt lgkmcnt(0)
	global_load_dword v1, v1, s[4:5]
	s_mov_b64 s[4:5], s[0:1]
	s_waitcnt vmcnt(2)
	v_mul_f32_e32 v18, v3, v4
	s_nop 1
	v_mov_b32_dpp v5, v18 quad_perm:[1,0,3,2] row_mask:0xf bank_mask:0xf
	v_fmac_f32_e32 v5, v3, v4
	s_nop 1
	v_mov_b32_dpp v3, v5 quad_perm:[2,3,0,1] row_mask:0xf bank_mask:0xf
	v_add_f32_e32 v3, v5, v3
	s_nop 1
	v_mov_b32_dpp v5, v3 row_shl:4 row_mask:0xf bank_mask:0x5
	v_mov_b32_dpp v5, v3 row_shr:4 row_mask:0xf bank_mask:0xa
	v_add_f32_e32 v3, v3, v5
	s_nop 1
	v_mov_b32_dpp v5, v3 row_ror:8 row_mask:0xf bank_mask:0xf
	s_waitcnt vmcnt(0)
	v_mul_f32_e32 v18, v11, v1
	s_nop 1
	v_mov_b32_dpp v12, v18 quad_perm:[1,0,3,2] row_mask:0xf bank_mask:0xf
	v_add_f32_e32 v3, v3, v5
	v_mov_b32_e32 v5, v3
	v_mov_b32_e32 v120, v3
	s_nop 1
	v_permlane16_swap_b32_e32 v5, v120
	v_cndmask_b32_e64 v5, v120, v5, s[98:99]
	v_fmac_f32_e32 v12, v11, v1
	s_nop 1
	v_mov_b32_dpp v1, v12 quad_perm:[2,3,0,1] row_mask:0xf bank_mask:0xf
	v_add_f32_e32 v1, v12, v1
	s_nop 1
	v_mov_b32_dpp v4, v1 row_shl:4 row_mask:0xf bank_mask:0x5
	v_mov_b32_dpp v4, v1 row_shr:4 row_mask:0xf bank_mask:0xa
	v_add_f32_e32 v1, v1, v4
	s_nop 1
	v_mov_b32_dpp v4, v1 row_ror:8 row_mask:0xf bank_mask:0xf
	v_add_f32_e32 v1, v1, v4
	v_mov_b32_e32 v6, v1
	v_mov_b32_e32 v120, v1
	s_nop 1
	v_permlane16_swap_b32_e32 v6, v120
	v_cndmask_b32_e64 v6, v120, v6, s[98:99]
	v_add_f32_e32 v4, v3, v5
	v_mov_b32_e32 v5, v4
	v_mov_b32_e32 v120, v4
	s_nop 1
	v_permlane32_swap_b32_e32 v5, v120
	v_cndmask_b32_e64 v5, v120, v5, s[100:101]
	v_add_f32_e32 v1, v1, v6
	v_mov_b32_e32 v3, v1
	v_mov_b32_e32 v120, v1
	s_nop 1
	v_permlane32_swap_b32_e32 v3, v120
	v_cndmask_b32_e64 v3, v120, v3, s[100:101]
	s_cbranch_vccz .LBB0_599
	s_load_dwordx2 s[4:5], s[4:5], 0x48
	v_lshlrev_b32_e32 v0, 5, v0
	v_and_b32_e32 v0, 0x1e0, v0
	s_waitcnt lgkmcnt(0)
	v_add_f32_e32 v4, v4, v5
	v_add_f32_e32 v16, v1, v3
	global_load_dwordx4 v[6:9], v0, s[4:5]
	global_load_dwordx4 v[10:13], v0, s[4:5] offset:16
	s_mov_b32 s5, 0x3fb8aa3b
	v_mul_f32_e32 v3, 0x3fb8aa3b, v4
	v_mul_f32_e32 v17, 0x3fb8aa3b, v16
	v_fma_f32 v18, v4, s5, -v3
	v_rndne_f32_e32 v19, v3
	v_fma_f32 v20, v16, s5, -v17
	v_rndne_f32_e32 v21, v17
	v_fmac_f32_e32 v18, 0x32a5705f, v4
	v_sub_f32_e32 v3, v3, v19
	v_fmac_f32_e32 v20, 0x32a5705f, v16
	v_sub_f32_e32 v17, v17, v21
	v_add_f32_e32 v3, v3, v18
	v_cvt_i32_f32_e32 v19, v19
	v_add_f32_e32 v17, v17, v20
	v_exp_f32_e32 v18, v3
	v_cvt_i32_f32_e32 v21, v21
	v_exp_f32_e32 v17, v17
	s_mov_b32 s17, 0xc2ce8ed0
	v_ldexp_f32 v18, v18, v19
	v_cmp_ngt_f32_e32 vcc, s17, v4
	s_mov_b32 s18, 0x42b17218
	v_ldexp_f32 v17, v17, v21
	v_cndmask_b32_e32 v18, 0, v18, vcc
	v_cmp_ngt_f32_e32 vcc, s17, v16
	v_mov_b32_e32 v5, 0x7f800000
	s_ashr_i32 s35, s34, 31
	v_cndmask_b32_e32 v17, 0, v17, vcc
	v_cmp_nlt_f32_e32 vcc, s18, v4
	s_lshl_b64 s[12:13], s[34:35], 10
	s_mov_b32 s4, 0x3f4ccccd
	v_cndmask_b32_e32 v4, v5, v18, vcc
	v_cmp_nlt_f32_e32 vcc, s18, v16
	v_lshlrev_b32_e32 v0, 3, v2
	s_mov_b64 s[10:11], 0x20500000
	v_cndmask_b32_e32 v5, v5, v17, vcc
	v_sub_f32_e32 v4, v4, v5
	s_ashr_i32 s31, s30, 31
	v_lshl_or_b32 v2, v2, 4, s12
	v_mov_b32_e32 v3, s13
	v_add_f32_e32 v4, 0x3e4ccccc, v4
	v_mov_b32_e32 v1, 0
	s_mov_b32 s3, 0x20500000
	s_mov_b32 s14, 0xffff0000
	v_mov_b32_e32 v14, 0x3727c5ac
	s_mov_b32 s15, 0xf800000
	v_mov_b32_e32 v15, 0x260
	s_movk_i32 s16, 0x7fff
	s_lshl_b64 s[6:7], s[30:31], 10
	v_lshlrev_b32_e32 v0, 1, v0
	v_lshl_add_u64 v[2:3], v[2:3], 0, s[10:11]
	v_mov_b32_e32 v5, v4
	s_mov_b32 s17, s34
	s_waitcnt vmcnt(1)
	v_mov_b32_e32 v16, v6
	v_mov_b32_e32 v17, v8
	v_mov_b32_e32 v8, v7
	s_waitcnt vmcnt(0)
	v_mov_b32_e32 v18, v10
	v_mov_b32_e32 v19, v12
	v_mov_b32_e32 v12, v11
	v_pk_mul_f32 v[6:7], v[16:17], s[4:5] op_sel_hi:[1,0]
	v_pk_mul_f32 v[8:9], v[8:9], s[4:5] op_sel_hi:[1,0]
	v_pk_mul_f32 v[10:11], v[18:19], s[4:5] op_sel_hi:[1,0]
	v_pk_mul_f32 v[12:13], v[12:13], s[4:5] op_sel_hi:[1,0]
	s_load_dwordx2 s[42:43], s[0:1], 0xc0
	s_waitcnt lgkmcnt(0)
	v_lshl_add_u64 v[48:49], s[42:43], 0, v[2:3]
	global_load_dwordx4 v[40:43], v[48:49], off
	s_add_i32 s40, s17, 0x4000
	s_ashr_i32 s41, s40, 31
	s_lshl_b64 s[40:41], s[40:41], 10
	s_add_u32 s40, s42, s40
	s_addc_u32 s41, s43, s41
	v_lshl_add_u64 v[50:51], s[40:41], 0, v[0:1]
	v_add_co_u32_e32 v50, vcc, s3, v50
	s_nop 1
	v_addc_co_u32_e32 v51, vcc, 0, v51, vcc
	global_load_dwordx4 v[44:47], v[50:51], off
	s_waitcnt vmcnt(0)
; __device__ __forceinline__ float shx(float v, int o) { const int l = lane_now(); return __int_as_float(__builtin_amdgcn_ds_bpermute((l ^ o) << 2, __float_as_int(v))); }
; __device__ __forceinline__ float bf_lo(unsigned w) { return __uint_as_float(w << 16); }
; __device__ __forceinline__ float bf_hi(unsigned w) { return __uint_as_float(w & 0xffff0000u); }
; __device__ __forceinline__ unsigned pk2(float lo, float hi) { return f2bf(lo) | (f2bf(hi) << 16); }
; template <int l, int SEL> __device__ __forceinline__ void layer_body(const Args& args, LAS unsigned char* ldsp, unsigned char* lds, const int G, const int bx, const int vcu, const int wv) {
;     ...
;             for (int row = gw; row < M; row += NGW) {
;                 const v4u a = *(const v4u*)(q_odiff + (size_t)row * 512 + 8 * lane), b = *(const v4u*)(q_odiff + (size_t)(M + row) * 512 + 8 * lane);
;                 float o[8]; const unsigned aw[4] = {a.x, a.y, a.z, a.w}, bw[4] = {b.x, b.y, b.z, b.w};
; #pragma unroll
;                 for (int i = 0; i < 4; ++i) { o[2 * i] = pg8::bf_lo(aw[i]) - lam * pg8::bf_lo(bw[i]); o[2 * i + 1] = pg8::bf_hi(aw[i]) - lam * pg8::bf_hi(bw[i]); }
;                 float ss = 0.f;
; #pragma unroll
;                 for (int i = 0; i < 8; ++i) ss += o[i] * o[i];
;                 ss += shx(ss, 1); ss += shx(ss, 2); ss += shx(ss, 4); ss += shx(ss, 8);
;                 const float r = 1.f / sqrtf(ss * (1.f / 128.f) + SUBLN_EPS);
;                 v4u w; w.x = pk2(o[0] * r * gsc[0], o[1] * r * gsc[1]); w.y = pk2(o[2] * r * gsc[2], o[3] * r * gsc[3]); w.z = pk2(o[4] * r * gsc[4], o[5] * r * gsc[5]); w.w = pk2(o[6] * r * gsc[6], o[7] * r * gsc[7]);
;                 *(v4u*)(q_yatt + (size_t)(M + row) * 512 + 8 * lane) = w;
.LBB0_598:
	s_waitcnt vmcnt(1)
	v_mov_b64_e32 v[16:17], v[40:41]
	v_mov_b64_e32 v[18:19], v[42:43]
	v_mov_b64_e32 v[20:21], v[44:45]
	v_mov_b64_e32 v[22:23], v[46:47]
	s_mov_b64 s[10:11], s[0:1]
	s_load_dwordx2 s[10:11], s[10:11], 0xc0
	s_mov_b64 s[4:5], s[0:1]
	s_add_i32 s12, s17, 0x4000
	s_ashr_i32 s13, s12, 31
	s_lshl_b64 s[12:13], s[12:13], 10
	s_waitcnt lgkmcnt(0)
	s_load_dwordx2 s[4:5], s[4:5], 0xc0
	s_mov_b64 s[18:19], s[0:1]
	v_lshl_add_u64 v[2:3], v[2:3], 0, s[6:7]
	s_waitcnt lgkmcnt(0)
	s_add_i32 s40, s17, s30
	s_cmpk_gt_i32 s40, 0x3fff
	s_cbranch_scc1 .Lp2bpf_LBB0_598
	v_lshl_add_u64 v[48:49], s[10:11], 0, v[2:3]
	global_load_dwordx4 v[40:43], v[48:49], off
	s_add_i32 s40, s40, 0x4000
	s_ashr_i32 s41, s40, 31
	s_lshl_b64 s[40:41], s[40:41], 10
	s_add_u32 s40, s10, s40
	s_addc_u32 s41, s11, s41
	v_lshl_add_u64 v[50:51], s[40:41], 0, v[0:1]
	v_add_co_u32_e32 v50, vcc, s3, v50
	s_nop 1
	v_addc_co_u32_e32 v51, vcc, 0, v51, vcc
	global_load_dwordx4 v[44:47], v[50:51], off
.Lp2bpf_LBB0_598:
	v_lshlrev_b32_e32 v29, 16, v19
	v_mbcnt_lo_u32_b32 v24, -1, 0
	v_mbcnt_hi_u32_b32 v24, -1, v24
	v_mbcnt_lo_u32_b32 v25, -1, 0
	v_mbcnt_hi_u32_b32 v25, -1, v25
	v_mbcnt_lo_u32_b32 v26, -1, 0
	v_mbcnt_hi_u32_b32 v26, -1, v26
	v_mbcnt_lo_u32_b32 v27, -1, 0
	v_mbcnt_hi_u32_b32 v27, -1, v27
	v_lshlrev_b32_e32 v28, 16, v18
	v_lshlrev_b32_e32 v26, 2, v26
	v_lshlrev_b32_e32 v27, 2, v27
	v_xor_b32_e32 v36, 16, v26
	v_xor_b32_e32 v37, 32, v27
	v_lshlrev_b32_e32 v27, 16, v17
	v_lshlrev_b32_e32 v26, 16, v16
	v_and_b32_e32 v17, 0xffff0000, v17
	v_and_b32_e32 v16, 0xffff0000, v16
	v_and_b32_e32 v19, 0xffff0000, v19
	v_and_b32_e32 v18, 0xffff0000, v18
	v_lshlrev_b32_e32 v24, 2, v24
	v_xor_b32_e32 v34, 4, v24
	v_lshlrev_b32_e32 v25, 2, v25
	v_xor_b32_e32 v35, 8, v25
	s_load_dwordx2 s[4:5], s[18:19], 0xc0
	s_waitcnt lgkmcnt(0)
	s_add_u32 s4, s4, s12
	s_addc_u32 s5, s5, s13
	v_lshl_add_u64 v[24:25], s[4:5], 0, v[0:1]
	s_add_i32 s17, s17, s30
	s_cmpk_gt_i32 s17, 0x3fff
	v_lshlrev_b32_e32 v31, 16, v21
	v_lshlrev_b32_e32 v30, 16, v20
	v_and_b32_e32 v21, 0xffff0000, v21
	v_and_b32_e32 v20, 0xffff0000, v20
	v_lshlrev_b32_e32 v33, 16, v23
	v_lshlrev_b32_e32 v32, 16, v22
	v_and_b32_e32 v23, 0xffff0000, v23
	v_and_b32_e32 v22, 0xffff0000, v22
	v_pk_fma_f32 v[26:27], v[4:5], v[30:31], v[26:27] neg_lo:[1,0,0] neg_hi:[1,0,0]
	v_pk_fma_f32 v[16:17], v[4:5], v[20:21], v[16:17] neg_lo:[1,0,0] neg_hi:[1,0,0]
	v_pk_fma_f32 v[20:21], v[4:5], v[32:33], v[28:29] neg_lo:[1,0,0] neg_hi:[1,0,0]
	v_pk_fma_f32 v[18:19], v[4:5], v[22:23], v[18:19] neg_lo:[1,0,0] neg_hi:[1,0,0]
	v_pk_mul_f32 v[22:23], v[26:27], v[26:27]
	v_pk_mul_f32 v[28:29], v[16:17], v[16:17]
	v_mov_b32_e32 v30, v18
	v_add_f32_e32 v22, v22, v28
	v_mov_b32_e32 v31, v20
	v_add_f32_e32 v22, v23, v22
	v_pk_mul_f32 v[30:31], v[30:31], v[30:31]
	v_add_f32_e32 v22, v29, v22
	v_mov_b32_e32 v32, v19
	v_mov_b32_e32 v33, v21
	v_add_f32_e32 v22, v31, v22
	v_pk_mul_f32 v[32:33], v[32:33], v[32:33]
	v_add_f32_e32 v22, v30, v22
	v_add_f32_e32 v22, v33, v22
	v_add_f32_e32 v22, v32, v22
	s_nop 1
	v_mov_b32_dpp v23, v22 quad_perm:[1,0,3,2] row_mask:0xf bank_mask:0xf
	v_add_f32_e32 v22, v22, v23
	s_nop 1
	v_mov_b32_dpp v23, v22 quad_perm:[2,3,0,1] row_mask:0xf bank_mask:0xf
	v_add_f32_e32 v22, v22, v23
	s_nop 1
	v_mov_b32_dpp v23, v22 row_shl:4 row_mask:0xf bank_mask:0x5
	v_mov_b32_dpp v23, v22 row_shr:4 row_mask:0xf bank_mask:0xa
	v_add_f32_e32 v22, v22, v23
	s_nop 1
	v_mov_b32_dpp v23, v22 row_ror:8 row_mask:0xf bank_mask:0xf
	v_add_f32_e32 v22, v22, v23
	v_fmamk_f32 v22, v22, 0x3c000000, v14
	v_mul_f32_e32 v23, 0x4f800000, v22
	v_cmp_gt_f32_e32 vcc, s15, v22
	s_nop 1
	v_cndmask_b32_e32 v22, v22, v23, vcc
	v_sqrt_f32_e32 v23, v22
	s_nop 0
	v_add_u32_e32 v28, -1, v23
	v_add_u32_e32 v29, 1, v23
	v_fma_f32 v30, -v28, v23, v22
	v_fma_f32 v31, -v29, v23, v22
	v_cmp_ge_f32_e64 s[4:5], 0, v30
	s_nop 1
	v_cndmask_b32_e64 v23, v23, v28, s[4:5]
	v_cmp_lt_f32_e64 s[4:5], 0, v31
	s_nop 1
	v_cndmask_b32_e64 v23, v23, v29, s[4:5]
	v_mul_f32_e32 v28, 0x37800000, v23
	v_cndmask_b32_e32 v23, v23, v28, vcc
	v_cmp_class_f32_e32 vcc, v22, v15
	s_nop 1
	v_cndmask_b32_e32 v23, v23, v22, vcc
	v_div_scale_f32 v22, s[4:5], v23, v23, 1.0
	v_rcp_f32_e32 v29, v22
	v_div_scale_f32 v28, vcc, 1.0, v23, 1.0
	v_fma_f32 v30, -v22, v29, 1.0
	v_fmac_f32_e32 v29, v30, v29
	v_mul_f32_e32 v30, v28, v29
	v_fma_f32 v31, -v22, v30, v28
	v_fmac_f32_e32 v30, v31, v29
	v_fma_f32 v22, -v22, v30, v28
	v_div_fmas_f32 v28, v22, v29, v30
	v_add_co_u32_e32 v22, vcc, 0x1e500000, v24
	v_div_fixup_f32 v24, v28, v23, 1.0
	v_pk_mul_f32 v[26:27], v[26:27], v[24:25] op_sel_hi:[1,0]
	v_pk_mul_f32 v[20:21], v[20:21], v[24:25] op_sel_hi:[1,0]
	v_addc_co_u32_e32 v23, vcc, 0, v25, vcc
	v_pk_mul_f32 v[16:17], v[16:17], v[24:25] op_sel_hi:[1,0]
	v_pk_mul_f32 v[18:19], v[18:19], v[24:25] op_sel_hi:[1,0]
	v_pk_mul_f32 v[24:25], v[6:7], v[26:27]
	v_pk_mul_f32 v[20:21], v[10:11], v[20:21]
	v_pk_mul_f32 v[16:17], v[8:9], v[16:17]
	v_pk_mul_f32 v[18:19], v[12:13], v[18:19]
	v_bfe_u32 v30, v24, 16, 1
	v_bfe_u32 v31, v25, 16, 1
	v_bfe_u32 v32, v20, 16, 1
	v_bfe_u32 v33, v21, 16, 1
	v_bfe_u32 v26, v19, 16, 1
	v_bfe_u32 v27, v18, 16, 1
	v_bfe_u32 v28, v17, 16, 1
	v_bfe_u32 v29, v16, 16, 1
	v_add3_u32 v21, v21, v33, s16
	v_add3_u32 v20, v20, v32, s16
	v_add3_u32 v25, v25, v31, s16
	v_add3_u32 v24, v24, v30, s16
	v_add3_u32 v16, v16, v29, s16
	v_add3_u32 v17, v17, v28, s16
	v_add3_u32 v18, v18, v27, s16
	v_add3_u32 v19, v19, v26, s16
	v_lshrrev_b32_e32 v24, 16, v24
	v_lshrrev_b32_e32 v25, 16, v25
	v_lshrrev_b32_e32 v20, 16, v20
	v_lshrrev_b32_e32 v21, 16, v21
	v_and_or_b32 v19, v19, s14, v21
	v_and_or_b32 v18, v18, s14, v20
	v_and_or_b32 v17, v17, s14, v25
	v_and_or_b32 v16, v16, s14, v24
	global_store_dwordx4 v[22:23], v[16:19], off
	s_cbranch_scc0 .LBB0_598

; #define in KArgIn()
; #define FRESH_IDS() const int tid = tid_fresh(wv), lane = tid & 63, wave = wv
; template <int l, int SEL> __device__ __forceinline__ void layer_body(const Args& args, LAS unsigned char* ldsp, unsigned char* lds, const int G, const int bx, const int vcu, const int wv) {
;     ...
;             FRESH_IDS();
;             const float lam_init = 0.8f - 0.6f * expf(-0.3f * (float)l);
;             const float a1 = wave_sum(in[5][l * 64 + lane] * in[6][l * 64 + lane]), a2 = wave_sum(in[7][l * 64 + lane] * in[8][l * 64 + lane]);
;             const float lam = expf(a1) - expf(a2) + lam_init;
;             const float* sg = in[9] + l * 128 + (lane & 15) * 8; float gsc[8];
; #pragma unroll
;             for (int i = 0; i < 8; ++i) gsc[i] = sg[i] * (1.f - lam_init);
;             const int gw = bx * NWAVES + wave, NGW = G * NWAVES;
;             for (int row = gw; row < M; row += NGW) {
;                 const v4u a = *(const v4u*)(q_odiff + (size_t)row * 512 + 8 * lane), b = *(const v4u*)(q_odiff + (size_t)(M + row) * 512 + 8 * lane);
.LBB0_1636:
	s_or_b64 exec, exec, s[8:9]
	s_mov_b64 s[8:9], s[0:1]
	s_waitcnt lgkmcnt(0)
	s_barrier
	v_mbcnt_lo_u32_b32 v0, -1, 0
	v_mbcnt_hi_u32_b32 v0, -1, v0
	s_load_dwordx2 s[8:9], s[8:9], 0x28
	v_and_b32_e32 v2, 63, v0
	v_lshlrev_b32_e32 v1, 2, v2
	s_and_b64 vcc, exec, s[38:39]
	s_waitcnt lgkmcnt(0)
	global_load_dword v3, v1, s[8:9] offset:256
	s_mov_b64 s[8:9], s[0:1]
	s_load_dwordx2 s[8:9], s[8:9], 0x30
	s_waitcnt lgkmcnt(0)
	global_load_dword v4, v1, s[8:9] offset:256
	s_mov_b64 s[8:9], s[0:1]
	s_load_dwordx2 s[8:9], s[8:9], 0x38
	s_waitcnt lgkmcnt(0)
	global_load_dword v11, v1, s[8:9] offset:256
	s_mov_b64 s[8:9], s[0:1]
	s_load_dwordx2 s[8:9], s[8:9], 0x40
	s_waitcnt lgkmcnt(0)
	global_load_dword v1, v1, s[8:9] offset:256
	s_mov_b64 s[8:9], s[0:1]
	s_waitcnt vmcnt(2)
	v_mul_f32_e32 v18, v3, v4
	s_nop 1
	v_mov_b32_dpp v5, v18 quad_perm:[1,0,3,2] row_mask:0xf bank_mask:0xf
	v_fmac_f32_e32 v5, v3, v4
	s_nop 1
	v_mov_b32_dpp v3, v5 quad_perm:[2,3,0,1] row_mask:0xf bank_mask:0xf
	v_add_f32_e32 v3, v5, v3
	s_nop 1
	v_mov_b32_dpp v5, v3 row_shl:4 row_mask:0xf bank_mask:0x5
	v_mov_b32_dpp v5, v3 row_shr:4 row_mask:0xf bank_mask:0xa
	v_add_f32_e32 v3, v3, v5
	s_nop 1
	v_mov_b32_dpp v5, v3 row_ror:8 row_mask:0xf bank_mask:0xf
	s_waitcnt vmcnt(0)
	v_mul_f32_e32 v18, v11, v1
	s_nop 1
	v_mov_b32_dpp v12, v18 quad_perm:[1,0,3,2] row_mask:0xf bank_mask:0xf
	v_add_f32_e32 v3, v3, v5
	v_mov_b32_e32 v5, v3
	v_mov_b32_e32 v120, v3
	s_nop 1
	v_permlane16_swap_b32_e32 v5, v120
	v_cndmask_b32_e64 v5, v120, v5, s[98:99]
	v_fmac_f32_e32 v12, v11, v1
	s_nop 1
	v_mov_b32_dpp v1, v12 quad_perm:[2,3,0,1] row_mask:0xf bank_mask:0xf
	v_add_f32_e32 v1, v12, v1
	s_nop 1
	v_mov_b32_dpp v4, v1 row_shl:4 row_mask:0xf bank_mask:0x5
	v_mov_b32_dpp v4, v1 row_shr:4 row_mask:0xf bank_mask:0xa
	v_add_f32_e32 v1, v1, v4
	s_nop 1
	v_mov_b32_dpp v4, v1 row_ror:8 row_mask:0xf bank_mask:0xf
	v_add_f32_e32 v1, v1, v4
	v_mov_b32_e32 v6, v1
	v_mov_b32_e32 v120, v1
	s_nop 1
	v_permlane16_swap_b32_e32 v6, v120
	v_cndmask_b32_e64 v6, v120, v6, s[98:99]
	v_add_f32_e32 v4, v3, v5
	v_mov_b32_e32 v5, v4
	v_mov_b32_e32 v120, v4
	s_nop 1
	v_permlane32_swap_b32_e32 v5, v120
	v_cndmask_b32_e64 v5, v120, v5, s[100:101]
	v_add_f32_e32 v1, v1, v6
	v_mov_b32_e32 v3, v1
	v_mov_b32_e32 v120, v1
	s_nop 1
	v_permlane32_swap_b32_e32 v3, v120
	v_cndmask_b32_e64 v3, v120, v3, s[100:101]
	s_cbranch_vccz .LBB0_1639
	s_load_dwordx2 s[8:9], s[8:9], 0x48
	v_lshlrev_b32_e32 v0, 5, v0
	v_and_b32_e32 v0, 0x1e0, v0
	s_waitcnt lgkmcnt(0)
	v_add_f32_e32 v4, v4, v5
	v_add_f32_e32 v16, v1, v3
	global_load_dwordx4 v[6:9], v0, s[8:9] offset:512
	global_load_dwordx4 v[10:13], v0, s[8:9] offset:528
	s_mov_b32 s9, 0x3fb8aa3b
	v_mul_f32_e32 v3, 0x3fb8aa3b, v4
	v_mul_f32_e32 v17, 0x3fb8aa3b, v16
	v_fma_f32 v18, v4, s9, -v3
	v_rndne_f32_e32 v19, v3
	v_fma_f32 v20, v16, s9, -v17
	v_rndne_f32_e32 v21, v17
	v_fmac_f32_e32 v18, 0x32a5705f, v4
	v_sub_f32_e32 v3, v3, v19
	v_fmac_f32_e32 v20, 0x32a5705f, v16
	v_sub_f32_e32 v17, v17, v21
	v_add_f32_e32 v3, v3, v18
	v_cvt_i32_f32_e32 v19, v19
	v_add_f32_e32 v17, v17, v20
	v_exp_f32_e32 v18, v3
	v_cvt_i32_f32_e32 v21, v21
	v_exp_f32_e32 v17, v17
	s_mov_b32 s19, 0xc2ce8ed0
	v_ldexp_f32 v18, v18, v19
	v_cmp_ngt_f32_e32 vcc, s19, v4
	s_mov_b32 s20, 0x42b17218
	v_ldexp_f32 v17, v17, v21
	v_cndmask_b32_e32 v18, 0, v18, vcc
	v_cmp_ngt_f32_e32 vcc, s19, v16
	v_mov_b32_e32 v5, 0x7f800000
	s_ashr_i32 s35, s34, 31
	v_cndmask_b32_e32 v17, 0, v17, vcc
	v_cmp_nlt_f32_e32 vcc, s20, v4
	s_lshl_b64 s[14:15], s[34:35], 10
	s_mov_b32 s8, 0x3f24fd5c
	v_cndmask_b32_e32 v4, v5, v18, vcc
	v_cmp_nlt_f32_e32 vcc, s20, v16
	v_lshlrev_b32_e32 v0, 3, v2
	s_mov_b64 s[12:13], 0x20500000
	v_cndmask_b32_e32 v5, v5, v17, vcc
	v_sub_f32_e32 v4, v4, v5
	s_ashr_i32 s31, s30, 31
	v_lshl_or_b32 v2, v2, 4, s14
	v_mov_b32_e32 v3, s15
	v_add_f32_e32 v4, 0x3eb60549, v4
	v_mov_b32_e32 v1, 0
	s_mov_b32 s3, 0x20500000
	s_mov_b32 s16, 0xffff0000
	v_mov_b32_e32 v14, 0x3727c5ac
	s_mov_b32 s17, 0xf800000
	v_mov_b32_e32 v15, 0x260
	s_movk_i32 s18, 0x7fff
	s_lshl_b64 s[10:11], s[30:31], 10
	v_lshlrev_b32_e32 v0, 1, v0
	v_lshl_add_u64 v[2:3], v[2:3], 0, s[12:13]
	v_mov_b32_e32 v5, v4
	s_mov_b32 s19, s34
	s_waitcnt vmcnt(1)
	v_mov_b32_e32 v16, v6
	v_mov_b32_e32 v17, v8
	v_mov_b32_e32 v8, v7
	s_waitcnt vmcnt(0)
	v_mov_b32_e32 v18, v10
	v_mov_b32_e32 v19, v12
	v_mov_b32_e32 v12, v11
	v_pk_mul_f32 v[6:7], v[16:17], s[8:9] op_sel_hi:[1,0]
	v_pk_mul_f32 v[8:9], v[8:9], s[8:9] op_sel_hi:[1,0]
	v_pk_mul_f32 v[10:11], v[18:19], s[8:9] op_sel_hi:[1,0]
	v_pk_mul_f32 v[12:13], v[12:13], s[8:9] op_sel_hi:[1,0]
	s_load_dwordx2 s[42:43], s[0:1], 0xc0
	s_waitcnt lgkmcnt(0)
	v_lshl_add_u64 v[48:49], s[42:43], 0, v[2:3]
	global_load_dwordx4 v[40:43], v[48:49], off
	s_add_i32 s40, s19, 0x4000
	s_ashr_i32 s41, s40, 31
	s_lshl_b64 s[40:41], s[40:41], 10
	s_add_u32 s40, s42, s40
	s_addc_u32 s41, s43, s41
	v_lshl_add_u64 v[50:51], s[40:41], 0, v[0:1]
	v_add_co_u32_e32 v50, vcc, s3, v50
	s_nop 1
	v_addc_co_u32_e32 v51, vcc, 0, v51, vcc
	global_load_dwordx4 v[44:47], v[50:51], off
	s_waitcnt vmcnt(0)
; __device__ __forceinline__ float shx(float v, int o) { const int l = lane_now(); return __int_as_float(__builtin_amdgcn_ds_bpermute((l ^ o) << 2, __float_as_int(v))); }
; __device__ __forceinline__ float bf_lo(unsigned w) { return __uint_as_float(w << 16); }
; __device__ __forceinline__ float bf_hi(unsigned w) { return __uint_as_float(w & 0xffff0000u); }
; __device__ __forceinline__ unsigned pk2(float lo, float hi) { return f2bf(lo) | (f2bf(hi) << 16); }
; template <int l, int SEL> __device__ __forceinline__ void layer_body(const Args& args, LAS unsigned char* ldsp, unsigned char* lds, const int G, const int bx, const int vcu, const int wv) {
;     ...
;             for (int row = gw; row < M; row += NGW) {
;                 const v4u a = *(const v4u*)(q_odiff + (size_t)row * 512 + 8 * lane), b = *(const v4u*)(q_odiff + (size_t)(M + row) * 512 + 8 * lane);
;                 float o[8]; const unsigned aw[4] = {a.x, a.y, a.z, a.w}, bw[4] = {b.x, b.y, b.z, b.w};
; #pragma unroll
;                 for (int i = 0; i < 4; ++i) { o[2 * i] = pg8::bf_lo(aw[i]) - lam * pg8::bf_lo(bw[i]); o[2 * i + 1] = pg8::bf_hi(aw[i]) - lam * pg8::bf_hi(bw[i]); }
;                 float ss = 0.f;
; #pragma unroll
;                 for (int i = 0; i < 8; ++i) ss += o[i] * o[i];
;                 ss += shx(ss, 1); ss += shx(ss, 2); ss += shx(ss, 4); ss += shx(ss, 8);
;                 const float r = 1.f / sqrtf(ss * (1.f / 128.f) + SUBLN_EPS);
;                 v4u w; w.x = pk2(o[0] * r * gsc[0], o[1] * r * gsc[1]); w.y = pk2(o[2] * r * gsc[2], o[3] * r * gsc[3]); w.z = pk2(o[4] * r * gsc[4], o[5] * r * gsc[5]); w.w = pk2(o[6] * r * gsc[6], o[7] * r * gsc[7]);
;                 *(v4u*)(q_yatt + (size_t)(M + row) * 512 + 8 * lane) = w;
.LBB0_1638:
	s_waitcnt vmcnt(1)
	v_mov_b64_e32 v[16:17], v[40:41]
	v_mov_b64_e32 v[18:19], v[42:43]
	v_mov_b64_e32 v[20:21], v[44:45]
	v_mov_b64_e32 v[22:23], v[46:47]
	s_mov_b64 s[12:13], s[0:1]
	s_load_dwordx2 s[12:13], s[12:13], 0xc0
	s_mov_b64 s[8:9], s[0:1]
	s_add_i32 s14, s19, 0x4000
	s_ashr_i32 s15, s14, 31
	s_lshl_b64 s[14:15], s[14:15], 10
	s_waitcnt lgkmcnt(0)
	s_load_dwordx2 s[8:9], s[8:9], 0xc0
	s_mov_b64 s[20:21], s[0:1]
	v_lshl_add_u64 v[2:3], v[2:3], 0, s[10:11]
	s_waitcnt lgkmcnt(0)
	s_add_i32 s40, s19, s30
	s_cmpk_gt_i32 s40, 0x3fff
	s_cbranch_scc1 .Lp2bpf_LBB0_1638
	v_lshl_add_u64 v[48:49], s[12:13], 0, v[2:3]
	global_load_dwordx4 v[40:43], v[48:49], off
	s_add_i32 s40, s40, 0x4000
	s_ashr_i32 s41, s40, 31
	s_lshl_b64 s[40:41], s[40:41], 10
	s_add_u32 s40, s12, s40
	s_addc_u32 s41, s13, s41
	v_lshl_add_u64 v[50:51], s[40:41], 0, v[0:1]
	v_add_co_u32_e32 v50, vcc, s3, v50
	s_nop 1
	v_addc_co_u32_e32 v51, vcc, 0, v51, vcc
	global_load_dwordx4 v[44:47], v[50:51], off
.Lp2bpf_LBB0_1638:
	v_lshlrev_b32_e32 v29, 16, v19
	v_mbcnt_lo_u32_b32 v24, -1, 0
	v_mbcnt_hi_u32_b32 v24, -1, v24
	v_mbcnt_lo_u32_b32 v25, -1, 0
	v_mbcnt_hi_u32_b32 v25, -1, v25
	v_mbcnt_lo_u32_b32 v26, -1, 0
	v_mbcnt_hi_u32_b32 v26, -1, v26
	v_mbcnt_lo_u32_b32 v27, -1, 0
	v_mbcnt_hi_u32_b32 v27, -1, v27
	v_lshlrev_b32_e32 v28, 16, v18
	v_lshlrev_b32_e32 v26, 2, v26
	v_lshlrev_b32_e32 v27, 2, v27
	v_xor_b32_e32 v36, 16, v26
	v_xor_b32_e32 v37, 32, v27
	v_lshlrev_b32_e32 v27, 16, v17
	v_lshlrev_b32_e32 v26, 16, v16
	v_and_b32_e32 v17, 0xffff0000, v17
	v_and_b32_e32 v16, 0xffff0000, v16
	v_and_b32_e32 v19, 0xffff0000, v19
	v_and_b32_e32 v18, 0xffff0000, v18
	v_lshlrev_b32_e32 v24, 2, v24
	v_xor_b32_e32 v34, 4, v24
	v_lshlrev_b32_e32 v25, 2, v25
	v_xor_b32_e32 v35, 8, v25
	s_load_dwordx2 s[8:9], s[20:21], 0xc0
	s_waitcnt lgkmcnt(0)
	s_add_u32 s8, s8, s14
	s_addc_u32 s9, s9, s15
	v_lshl_add_u64 v[24:25], s[8:9], 0, v[0:1]
	s_add_i32 s19, s19, s30
	s_cmpk_gt_i32 s19, 0x3fff
	v_lshlrev_b32_e32 v31, 16, v21
	v_lshlrev_b32_e32 v30, 16, v20
	v_and_b32_e32 v21, 0xffff0000, v21
	v_and_b32_e32 v20, 0xffff0000, v20
	v_lshlrev_b32_e32 v33, 16, v23
	v_lshlrev_b32_e32 v32, 16, v22
	v_and_b32_e32 v23, 0xffff0000, v23
	v_and_b32_e32 v22, 0xffff0000, v22
	v_pk_fma_f32 v[26:27], v[4:5], v[30:31], v[26:27] neg_lo:[1,0,0] neg_hi:[1,0,0]
	v_pk_fma_f32 v[16:17], v[4:5], v[20:21], v[16:17] neg_lo:[1,0,0] neg_hi:[1,0,0]
	v_pk_fma_f32 v[20:21], v[4:5], v[32:33], v[28:29] neg_lo:[1,0,0] neg_hi:[1,0,0]
	v_pk_fma_f32 v[18:19], v[4:5], v[22:23], v[18:19] neg_lo:[1,0,0] neg_hi:[1,0,0]
	v_pk_mul_f32 v[22:23], v[26:27], v[26:27]
	v_pk_mul_f32 v[28:29], v[16:17], v[16:17]
	v_mov_b32_e32 v30, v18
	v_add_f32_e32 v22, v22, v28
	v_mov_b32_e32 v31, v20
	v_add_f32_e32 v22, v23, v22
	v_pk_mul_f32 v[30:31], v[30:31], v[30:31]
	v_add_f32_e32 v22, v29, v22
	v_mov_b32_e32 v32, v19
	v_mov_b32_e32 v33, v21
	v_add_f32_e32 v22, v31, v22
	v_pk_mul_f32 v[32:33], v[32:33], v[32:33]
	v_add_f32_e32 v22, v30, v22
	v_add_f32_e32 v22, v33, v22
	v_add_f32_e32 v22, v32, v22
	s_nop 1
	v_mov_b32_dpp v23, v22 quad_perm:[1,0,3,2] row_mask:0xf bank_mask:0xf
	v_add_f32_e32 v22, v22, v23
	s_nop 1
	v_mov_b32_dpp v23, v22 quad_perm:[2,3,0,1] row_mask:0xf bank_mask:0xf
	v_add_f32_e32 v22, v22, v23
	s_nop 1
	v_mov_b32_dpp v23, v22 row_shl:4 row_mask:0xf bank_mask:0x5
	v_mov_b32_dpp v23, v22 row_shr:4 row_mask:0xf bank_mask:0xa
	v_add_f32_e32 v22, v22, v23
	s_nop 1
	v_mov_b32_dpp v23, v22 row_ror:8 row_mask:0xf bank_mask:0xf
	v_add_f32_e32 v22, v22, v23
	v_fmamk_f32 v22, v22, 0x3c000000, v14
	v_mul_f32_e32 v23, 0x4f800000, v22
	v_cmp_gt_f32_e32 vcc, s17, v22
	s_nop 1
	v_cndmask_b32_e32 v22, v22, v23, vcc
	v_sqrt_f32_e32 v23, v22
	s_nop 0
	v_add_u32_e32 v28, -1, v23
	v_add_u32_e32 v29, 1, v23
	v_fma_f32 v30, -v28, v23, v22
	v_fma_f32 v31, -v29, v23, v22
	v_cmp_ge_f32_e64 s[8:9], 0, v30
	s_nop 1
	v_cndmask_b32_e64 v23, v23, v28, s[8:9]
	v_cmp_lt_f32_e64 s[8:9], 0, v31
	s_nop 1
	v_cndmask_b32_e64 v23, v23, v29, s[8:9]
	v_mul_f32_e32 v28, 0x37800000, v23
	v_cndmask_b32_e32 v23, v23, v28, vcc
	v_cmp_class_f32_e32 vcc, v22, v15
	s_nop 1
	v_cndmask_b32_e32 v23, v23, v22, vcc
	v_div_scale_f32 v22, s[8:9], v23, v23, 1.0
	v_rcp_f32_e32 v29, v22
	v_div_scale_f32 v28, vcc, 1.0, v23, 1.0
	v_fma_f32 v30, -v22, v29, 1.0
	v_fmac_f32_e32 v29, v30, v29
	v_mul_f32_e32 v30, v28, v29
	v_fma_f32 v31, -v22, v30, v28
	v_fmac_f32_e32 v30, v31, v29
	v_fma_f32 v22, -v22, v30, v28
	v_div_fmas_f32 v28, v22, v29, v30
	v_add_co_u32_e32 v22, vcc, 0x1e500000, v24
	v_div_fixup_f32 v24, v28, v23, 1.0
	v_pk_mul_f32 v[26:27], v[26:27], v[24:25] op_sel_hi:[1,0]
	v_pk_mul_f32 v[20:21], v[20:21], v[24:25] op_sel_hi:[1,0]
	v_addc_co_u32_e32 v23, vcc, 0, v25, vcc
	v_pk_mul_f32 v[16:17], v[16:17], v[24:25] op_sel_hi:[1,0]
	v_pk_mul_f32 v[18:19], v[18:19], v[24:25] op_sel_hi:[1,0]
	v_pk_mul_f32 v[24:25], v[6:7], v[26:27]
	v_pk_mul_f32 v[20:21], v[10:11], v[20:21]
	v_pk_mul_f32 v[16:17], v[8:9], v[16:17]
	v_pk_mul_f32 v[18:19], v[12:13], v[18:19]
	v_bfe_u32 v30, v24, 16, 1
	v_bfe_u32 v31, v25, 16, 1
	v_bfe_u32 v32, v20, 16, 1
	v_bfe_u32 v33, v21, 16, 1
	v_bfe_u32 v26, v19, 16, 1
	v_bfe_u32 v27, v18, 16, 1
	v_bfe_u32 v28, v17, 16, 1
	v_bfe_u32 v29, v16, 16, 1
	v_add3_u32 v21, v21, v33, s18
	v_add3_u32 v20, v20, v32, s18
	v_add3_u32 v25, v25, v31, s18
	v_add3_u32 v24, v24, v30, s18
	v_add3_u32 v16, v16, v29, s18
	v_add3_u32 v17, v17, v28, s18
	v_add3_u32 v18, v18, v27, s18
	v_add3_u32 v19, v19, v26, s18
	v_lshrrev_b32_e32 v24, 16, v24
	v_lshrrev_b32_e32 v25, 16, v25
	v_lshrrev_b32_e32 v20, 16, v20
	v_lshrrev_b32_e32 v21, 16, v21
	v_and_or_b32 v19, v19, s16, v21
	v_and_or_b32 v18, v18, s16, v20
	v_and_or_b32 v17, v17, s16, v25
	v_and_or_b32 v16, v16, s16, v24
	global_store_dwordx4 v[22:23], v[16:19], off
	s_cbranch_scc0 .LBB0_1638
